# attention iteration tail: the duplicate vmcnt(0) in front of the combined wait and barrier removed
# baseline (speedup 1.0000x reference)
.LBB0_2760:
	s_add_i32 s21, s21, 0x8000
	s_add_i32 s20, s20, 64
	s_cmp_eq_u32 s16, s19
	s_waitcnt vmcnt(0) lgkmcnt(0)
	s_barrier
	s_cbranch_scc1 .LBB0_2780
